# adds: P2 prep job issues the conv-tap loads before the 18 row prefetch loads (their vmcnt(0) no longer drains the row prefetch)
# baseline (speedup 1.0000x reference)
; #define LAS __attribute__((address_space(3)))
; __device__ __forceinline__ float bf_lo(unsigned v) { return __uint_as_float(v << 16); }
; __device__ __forceinline__ float bf_hi(unsigned v) { return __uint_as_float(v & 0xffff0000u); }
; __device__ __forceinline__ float silu_f(float x) { return x * __builtin_amdgcn_rcpf(1.0f + __expf(-x)); }
; __device__ __forceinline__ void gdn_prep_job3(const float* gdn_conv, const bf16* GQKV, bf16* CHUNK, float* CD, LAS unsigned char* lds, int jb, int jb_next, int rslot, v4u (&xr)[18], int tid, int wave, int lane) {
;     ...
;     const float gl_ = gcL[63];
;     if (tid == 0) CD[jb] = expf(gl_);
;     { const int i = tid >> 3, seg = tid & 7;
;       const float g_i = gcL[i]; const float beta_i = betaL[i], eg_i = expf(g_i), kds_i = expf(gl_ - g_i); const float beg_i = beta_i * eg_i;
; #pragma unroll
;       for (int part = 0; part < 3; ++part) {
;           v4u xc[2], xp[2], xn[2];
;           xp[0] = xr[part * 6 + 0]; xp[1] = xr[part * 6 + 1]; xc[0] = xr[part * 6 + 2]; xc[1] = xr[part * 6 + 3]; xn[0] = xr[part * 6 + 4]; xn[1] = xr[part * 6 + 5];
;           const LAS float* w0 = wL + (part * 3) * 128 + seg * 16; const LAS float* w1 = w0 + 128; const LAS float* w2 = w0 + 256;
;           float y[16]; float ss = 0.f;
; #pragma unroll
;           for (int wd = 0; wd < 8; ++wd) { const unsigned up = xp[wd >> 2][wd & 3], uc = xc[wd >> 2][wd & 3], un = xn[wd >> 2][wd & 3]; const int e = 2 * wd;
;               const float a0 = silu_f(w0[e] * bf_lo(up) + w1[e] * bf_lo(uc) + w2[e] * bf_lo(un)); const float a1 = silu_f(w0[e + 1] * bf_hi(up) + w1[e + 1] * bf_hi(uc) + w2[e + 1] * bf_hi(un));
;               y[e] = a0; y[e + 1] = a1; ss += a0 * a0 + a1 * a1; }
;           float sc = 1.0f;
;           if (part < 2) { ss += __shfl_xor(ss, 1); ss += __shfl_xor(ss, 2); ss += __shfl_xor(ss, 4); sc = rsqrtf(ss + EPS) * (part == 0 ? 0.08838834764831845f : 1.0f); }
; #pragma unroll
;           for (int e = 0; e < 16; ++e) y[e] *= sc;
.LBB0_249:
	s_or_b64 exec, exec, s[18:19]
	v_ashrrev_i32_e32 v124, 3, v88
	v_lshl_add_u32 v2, v124, 2, s23
	ds_read2st64_b32 v[2:3], v2 offset1:1
	s_cmp_lg_u32 s22, 15
	s_cselect_b64 s[18:19], -1, 0
	s_add_i32 s20, s20, 1
	s_cmp_lt_i32 s20, s83
	s_waitcnt lgkmcnt(0)
	v_mul_f32_e32 v76, 0x3fb8aa3b, v2
	v_fma_f32 v77, v2, s80, -v76
	v_rndne_f32_e32 v78, v76
	v_fmac_f32_e32 v77, 0x32a5705f, v2
	v_sub_f32_e32 v76, v76, v78
	v_add_f32_e32 v76, v76, v77
	v_exp_f32_e32 v76, v76
	v_cvt_i32_f32_e32 v77, v78
	v_cmp_ngt_f32_e32 vcc, s81, v2
	v_sub_f32_e32 v1, v1, v2
	s_cselect_b64 s[20:21], -1, 0
	v_ldexp_f32 v76, v76, v77
	v_cndmask_b32_e32 v76, 0, v76, vcc
	v_cmp_nlt_f32_e32 vcc, s92, v2
	v_mul_f32_e32 v2, 0x3fb8aa3b, v1
	v_rndne_f32_e32 v77, v2
	v_cndmask_b32_e32 v90, v123, v76, vcc
	v_fma_f32 v76, v1, s80, -v2
	v_fmac_f32_e32 v76, 0x32a5705f, v1
	v_sub_f32_e32 v2, v2, v77
	v_add_f32_e32 v2, v2, v76
	v_exp_f32_e32 v2, v2
	v_cvt_i32_f32_e32 v76, v77
	s_and_b64 s[18:19], s[18:19], s[20:21]
	s_add_i32 s1, s0, s74
	s_and_b64 s[18:19], s[18:19], exec
	s_mul_hi_i32 s18, s0, 0x12000
	s_mul_i32 s0, s0, 0x12000
	v_and_b32_e32 v89, 7, v88
	s_cselect_b32 s1, s1, -1
	s_add_u32 s84, s33, s0
	v_ldexp_f32 v2, v2, v76
	v_cmp_ngt_f32_e32 vcc, s81, v1
	v_lshlrev_b32_e32 v76, 5, v89
	v_mul_lo_u32 v77, v124, s69
	v_lshlrev_b32_e32 v78, 7, v124
	s_addc_u32 s85, s82, s18
	v_cndmask_b32_e32 v2, 0, v2, vcc
	v_cmp_nlt_f32_e32 vcc, s92, v1
	v_lshlrev_b32_e32 v1, 4, v89
	v_add3_u32 v127, 0, v76, v77
	v_lshlrev_b32_e32 v77, 1, v124
	v_ashrrev_i32_e32 v79, 31, v78
	v_xor_b32_e32 v1, v1, v77
	v_lshl_add_u64 v[78:79], v[78:79], 1, s[84:85]
	v_mov_b32_e32 v77, v0
	v_lshl_add_u64 v[92:93], v[78:79], 0, v[76:77]
	v_xor_b32_e32 v76, 1, v114
	v_add_u32_e32 v77, 64, v115
	v_cndmask_b32_e32 v126, v123, v2, vcc
	v_cmp_lt_i32_e32 vcc, v76, v77
	v_lshl_add_u32 v2, v89, 6, 0
	v_add_u32_e32 v2, 0x1f000, v2
	v_cndmask_b32_e32 v76, v114, v76, vcc
	v_lshlrev_b32_e32 v130, 2, v76
	v_xor_b32_e32 v76, 2, v114
	v_cmp_lt_i32_e32 vcc, v76, v77
	s_waitcnt vmcnt(47)
	v_lshlrev_b32_e32 v132, 16, v7
	v_and_b32_e32 v133, 0xffff0000, v7
	v_cndmask_b32_e32 v76, v114, v76, vcc
	v_lshlrev_b32_e32 v129, 2, v76
	v_xor_b32_e32 v76, 4, v114
	v_cmp_lt_i32_e32 vcc, v76, v77
	s_waitcnt vmcnt(46)
	v_lshlrev_b32_e32 v98, 16, v23
	v_and_b32_e32 v99, 0xffff0000, v23
	v_cndmask_b32_e32 v76, v114, v76, vcc
	v_lshlrev_b32_e32 v128, 2, v76
	ds_read_b128 v[76:79], v2
	ds_read_b128 v[80:83], v2 offset:16
	ds_read_b128 v[84:87], v2 offset:32
	ds_read_b128 v[100:103], v2 offset:48
	ds_read_b128 v[104:107], v2 offset:560
	v_lshlrev_b32_e32 v136, 16, v11
	v_and_b32_e32 v137, 0xffff0000, v11
	v_lshlrev_b32_e32 v138, 16, v9
	v_and_b32_e32 v139, 0xffff0000, v9
	s_waitcnt lgkmcnt(0)
	v_pk_mul_f32 v[106:107], v[106:107], v[132:133]
	ds_read_b128 v[132:135], v2 offset:1072
	v_pk_fma_f32 v[98:99], v[102:103], v[98:99], v[106:107]
	v_lshlrev_b32_e32 v102, 16, v27
	v_and_b32_e32 v103, 0xffff0000, v27
	v_lshlrev_b32_e32 v106, 16, v6
	s_waitcnt lgkmcnt(0)
	v_pk_fma_f32 v[98:99], v[134:135], v[102:103], v[98:99]
	v_and_b32_e32 v107, 0xffff0000, v6
	v_mul_f32_e32 v91, 0xbfb8aa3b, v98
	v_exp_f32_e32 v91, v91
	v_pk_mul_f32 v[104:105], v[104:105], v[106:107]
	v_lshlrev_b32_e32 v134, 16, v5
	v_and_b32_e32 v135, 0xffff0000, v5
	v_add_f32_e32 v91, 1.0, v91
	v_rcp_f32_e32 v102, v91
	v_mul_f32_e32 v91, 0xbfb8aa3b, v99
	v_exp_f32_e32 v91, v91
	s_mov_b32 s0, 0x8000
	s_mov_b64 s[18:19], 0x8000
	v_lshl_add_u64 v[96:97], v[92:93], 0, s[18:19]
	v_add_f32_e32 v91, 1.0, v91
	v_rcp_f32_e32 v103, v91
	v_mul_f32_e32 v125, v3, v90
	v_mul_u32_u24_e32 v89, 0x900, v89
	s_cmp_lt_i32 s1, 0
	v_pk_mul_f32 v[98:99], v[98:99], v[102:103]
	v_lshlrev_b32_e32 v102, 16, v22
	v_and_b32_e32 v103, 0xffff0000, v22
	v_pk_fma_f32 v[100:101], v[100:101], v[102:103], v[104:105]
	v_lshlrev_b32_e32 v102, 16, v26
	v_and_b32_e32 v103, 0xffff0000, v26
	v_pk_fma_f32 v[100:101], v[132:133], v[102:103], v[100:101]
	v_mov_b32_e32 v105, v99
	v_mul_f32_e32 v91, 0xbfb8aa3b, v100
	v_exp_f32_e32 v91, v91
	v_lshlrev_b32_e32 v132, 16, v21
	v_and_b32_e32 v133, 0xffff0000, v21
	v_add_f32_e32 v91, 1.0, v91
	v_rcp_f32_e32 v102, v91
	v_mul_f32_e32 v91, 0xbfb8aa3b, v101
	v_exp_f32_e32 v91, v91
	s_nop 0
	v_add_f32_e32 v91, 1.0, v91
	v_rcp_f32_e32 v103, v91
	s_nop 0
	v_pk_mul_f32 v[100:101], v[100:101], v[102:103]
	s_nop 0
	v_mov_b32_e32 v104, v101
	v_mov_b32_e32 v102, v100
	v_mov_b32_e32 v103, v98
	v_pk_mul_f32 v[104:105], v[104:105], v[104:105]
	s_nop 0
	v_pk_fma_f32 v[102:103], v[102:103], v[102:103], v[104:105]
	ds_read_b128 v[104:107], v2 offset:544
	s_waitcnt lgkmcnt(0)
	v_pk_mul_f32 v[106:107], v[106:107], v[134:135]
	s_nop 0
	v_pk_fma_f32 v[86:87], v[86:87], v[132:133], v[106:107]
	ds_read_b128 v[132:135], v2 offset:1056
	v_lshlrev_b32_e32 v106, 16, v25
	v_and_b32_e32 v107, 0xffff0000, v25
	s_waitcnt lgkmcnt(0)
	v_pk_fma_f32 v[86:87], v[134:135], v[106:107], v[86:87]
	s_nop 0
	v_mul_f32_e32 v91, 0xbfb8aa3b, v86
	v_exp_f32_e32 v91, v91
	v_lshlrev_b32_e32 v134, 16, v4
	v_and_b32_e32 v135, 0xffff0000, v4
	v_pk_mul_f32 v[104:105], v[104:105], v[134:135]
	v_add_f32_e32 v91, 1.0, v91
	v_rcp_f32_e32 v106, v91
	v_mul_f32_e32 v91, 0xbfb8aa3b, v87
	v_exp_f32_e32 v91, v91
	s_nop 0
	v_add_f32_e32 v91, 1.0, v91
	v_rcp_f32_e32 v107, v91
	s_nop 0
	v_pk_mul_f32 v[86:87], v[86:87], v[106:107]
	v_lshlrev_b32_e32 v106, 16, v20
	v_and_b32_e32 v107, 0xffff0000, v20
	v_pk_fma_f32 v[84:85], v[84:85], v[106:107], v[104:105]
	v_lshlrev_b32_e32 v104, 16, v24
	v_and_b32_e32 v105, 0xffff0000, v24
	v_pk_fma_f32 v[84:85], v[132:133], v[104:105], v[84:85]
	ds_read_b128 v[132:135], v2 offset:528
	v_mul_f32_e32 v91, 0xbfb8aa3b, v84
	v_exp_f32_e32 v91, v91
	v_mov_b32_e32 v107, v87
	s_waitcnt lgkmcnt(0)
; #define LAS __attribute__((address_space(3)))
; __device__ __forceinline__ unsigned pk2(float lo, float hi) { const f32x2 v = {lo, hi}; const hwbf16x2 r = __builtin_convertvector(v, hwbf16x2); return __builtin_bit_cast(unsigned, r); }
; __device__ __forceinline__ float bf_lo(unsigned v) { return __uint_as_float(v << 16); }
; __device__ __forceinline__ float bf_hi(unsigned v) { return __uint_as_float(v & 0xffff0000u); }
; __device__ __forceinline__ float silu_f(float x) { return x * __builtin_amdgcn_rcpf(1.0f + __expf(-x)); }
; __device__ __forceinline__ void gdn_prep_job3(const float* gdn_conv, const bf16* GQKV, bf16* CHUNK, float* CD, LAS unsigned char* lds, int jb, int jb_next, int rslot, v4u (&xr)[18], int tid, int wave, int lane) {
;     ...
;           for (int wd = 0; wd < 8; ++wd) { const unsigned up = xp[wd >> 2][wd & 3], uc = xc[wd >> 2][wd & 3], un = xn[wd >> 2][wd & 3]; const int e = 2 * wd;
;               const float a0 = silu_f(w0[e] * bf_lo(up) + w1[e] * bf_lo(uc) + w2[e] * bf_lo(un)); const float a1 = silu_f(w0[e + 1] * bf_hi(up) + w1[e + 1] * bf_hi(uc) + w2[e + 1] * bf_hi(un));
;               y[e] = a0; y[e + 1] = a1; ss += a0 * a0 + a1 * a1; }
;           float sc = 1.0f;
;           if (part < 2) { ss += __shfl_xor(ss, 1); ss += __shfl_xor(ss, 2); ss += __shfl_xor(ss, 4); sc = rsqrtf(ss + EPS) * (part == 0 ? 0.08838834764831845f : 1.0f); }
; #pragma unroll
;           for (int e = 0; e < 16; ++e) y[e] *= sc;
;           if (part == 0) {
;               v4u o0, o1; o0.x = pk2(y[0], y[1]); o0.y = pk2(y[2], y[3]); o0.z = pk2(y[4], y[5]); o0.w = pk2(y[6], y[7]); o1.x = pk2(y[8], y[9]); o1.y = pk2(y[10], y[11]); o1.z = pk2(y[12], y[13]); o1.w = pk2(y[14], y[15]);
;               *(LAS v4u*)(qB + i * 136 + seg * 16) = o0; *(LAS v4u*)(qB + i * 136 + seg * 16 + 8) = o1;
;               v4u g0, g1; g0.x = pk2(y[0] * eg_i, y[1] * eg_i); g0.y = pk2(y[2] * eg_i, y[3] * eg_i); g0.z = pk2(y[4] * eg_i, y[5] * eg_i); g0.w = pk2(y[6] * eg_i, y[7] * eg_i);
;               g1.x = pk2(y[8] * eg_i, y[9] * eg_i); g1.y = pk2(y[10] * eg_i, y[11] * eg_i); g1.z = pk2(y[12] * eg_i, y[13] * eg_i); g1.w = pk2(y[14] * eg_i, y[15] * eg_i);
;               *(v4u*)(cb + CH_QD + i * 128 + seg * 16) = g0; *(v4u*)(cb + CH_QD + i * 128 + seg * 16 + 8) = g1;
	v_pk_mul_f32 v[134:135], v[134:135], v[136:137]
	v_add_f32_e32 v91, 1.0, v91
	v_rcp_f32_e32 v104, v91
	v_mul_f32_e32 v91, 0xbfb8aa3b, v85
	v_exp_f32_e32 v91, v91
	s_nop 0
	v_add_f32_e32 v91, 1.0, v91
	v_rcp_f32_e32 v105, v91
	s_nop 0
	v_pk_mul_f32 v[84:85], v[84:85], v[104:105]
	s_nop 0
	v_mov_b32_e32 v106, v85
	v_mov_b32_e32 v104, v84
	v_mov_b32_e32 v105, v86
	v_pk_mul_f32 v[106:107], v[106:107], v[106:107]
	s_nop 0
	v_pk_fma_f32 v[104:105], v[104:105], v[104:105], v[106:107]
	v_lshlrev_b32_e32 v106, 16, v19
	v_and_b32_e32 v107, 0xffff0000, v19
	v_pk_fma_f32 v[82:83], v[82:83], v[106:107], v[134:135]
	ds_read_b128 v[134:137], v2 offset:1040
	v_lshlrev_b32_e32 v106, 16, v15
	v_and_b32_e32 v107, 0xffff0000, v15
	s_waitcnt lgkmcnt(0)
	v_pk_fma_f32 v[82:83], v[136:137], v[106:107], v[82:83]
	s_nop 0
	v_mul_f32_e32 v91, 0xbfb8aa3b, v82
	v_exp_f32_e32 v91, v91
	v_lshlrev_b32_e32 v136, 16, v10
	v_and_b32_e32 v137, 0xffff0000, v10
	v_pk_mul_f32 v[132:133], v[132:133], v[136:137]
	v_add_f32_e32 v91, 1.0, v91
	v_rcp_f32_e32 v106, v91
	v_mul_f32_e32 v91, 0xbfb8aa3b, v83
	v_exp_f32_e32 v91, v91
	v_lshlrev_b32_e32 v136, 16, v17
	v_and_b32_e32 v137, 0xffff0000, v17
	v_add_f32_e32 v91, 1.0, v91
	v_rcp_f32_e32 v107, v91
	s_nop 0
	v_pk_mul_f32 v[82:83], v[82:83], v[106:107]
	v_lshlrev_b32_e32 v106, 16, v18
	v_and_b32_e32 v107, 0xffff0000, v18
	v_pk_fma_f32 v[80:81], v[80:81], v[106:107], v[132:133]
	v_lshlrev_b32_e32 v106, 16, v14
	v_and_b32_e32 v107, 0xffff0000, v14
	v_pk_fma_f32 v[80:81], v[134:135], v[106:107], v[80:81]
	v_mov_b32_e32 v133, v83
	v_mul_f32_e32 v91, 0xbfb8aa3b, v80
	v_exp_f32_e32 v91, v91
	s_nop 0
	v_add_f32_e32 v91, 1.0, v91
	v_rcp_f32_e32 v106, v91
	v_mul_f32_e32 v91, 0xbfb8aa3b, v81
	v_exp_f32_e32 v91, v91
	s_nop 0
	v_add_f32_e32 v91, 1.0, v91
	v_rcp_f32_e32 v107, v91
	s_nop 0
	v_pk_mul_f32 v[80:81], v[80:81], v[106:107]
	s_nop 0
	v_mov_b32_e32 v132, v81
	v_mov_b32_e32 v106, v80
	v_mov_b32_e32 v107, v82
	v_pk_mul_f32 v[132:133], v[132:133], v[132:133]
	s_nop 0
	v_pk_fma_f32 v[106:107], v[106:107], v[106:107], v[132:133]
	ds_read_b128 v[132:135], v2 offset:512
	s_waitcnt lgkmcnt(0)
	v_pk_mul_f32 v[134:135], v[134:135], v[138:139]
	s_nop 0
	v_pk_fma_f32 v[78:79], v[78:79], v[136:137], v[134:135]
	ds_read_b128 v[134:137], v2 offset:1024
	v_lshlrev_b32_e32 v138, 16, v13
	v_and_b32_e32 v139, 0xffff0000, v13
	s_waitcnt lgkmcnt(0)
	v_pk_fma_f32 v[78:79], v[136:137], v[138:139], v[78:79]
	s_nop 0
	v_mul_f32_e32 v91, 0xbfb8aa3b, v78
	v_exp_f32_e32 v91, v91
	v_lshlrev_b32_e32 v138, 16, v8
	v_and_b32_e32 v139, 0xffff0000, v8
	v_pk_mul_f32 v[132:133], v[132:133], v[138:139]
	v_add_f32_e32 v91, 1.0, v91
	v_rcp_f32_e32 v136, v91
	v_mul_f32_e32 v91, 0xbfb8aa3b, v79
	v_exp_f32_e32 v91, v91
	s_nop 0
	v_add_f32_e32 v91, 1.0, v91
	v_rcp_f32_e32 v137, v91
	s_nop 0
	v_pk_mul_f32 v[78:79], v[78:79], v[136:137]
	v_lshlrev_b32_e32 v136, 16, v16
	v_and_b32_e32 v137, 0xffff0000, v16
	v_pk_fma_f32 v[76:77], v[76:77], v[136:137], v[132:133]
	v_lshlrev_b32_e32 v132, 16, v12
	v_and_b32_e32 v133, 0xffff0000, v12
	v_pk_fma_f32 v[76:77], v[134:135], v[132:133], v[76:77]
	v_mov_b32_e32 v135, v79
	v_mul_f32_e32 v91, 0xbfb8aa3b, v76
	v_exp_f32_e32 v91, v91
	s_nop 0
	v_add_f32_e32 v91, 1.0, v91
	v_rcp_f32_e32 v132, v91
	v_mul_f32_e32 v91, 0xbfb8aa3b, v77
	v_exp_f32_e32 v91, v91
	s_nop 0
	v_add_f32_e32 v91, 1.0, v91
	v_rcp_f32_e32 v133, v91
	s_nop 0
	v_pk_mul_f32 v[76:77], v[76:77], v[132:133]
	s_nop 0
	v_mov_b32_e32 v134, v77
	v_mov_b32_e32 v132, v76
	v_mov_b32_e32 v133, v78
	v_pk_mul_f32 v[134:135], v[134:135], v[134:135]
	s_nop 0
	v_pk_fma_f32 v[132:133], v[132:133], v[132:133], v[134:135]
	s_nop 0
	v_add_f32_e32 v91, v132, v133
	v_add_f32_e32 v91, v91, v106
	v_add_f32_e32 v91, v91, v107
	v_add_f32_e32 v91, v91, v104
	v_add_f32_e32 v91, v91, v105
	v_add_f32_e32 v91, v91, v102
	v_add_f32_e32 v91, v91, v103
	ds_bpermute_b32 v102, v130, v91
	s_waitcnt lgkmcnt(0)
	v_add_f32_e32 v91, v91, v102
	ds_bpermute_b32 v102, v129, v91
	s_waitcnt lgkmcnt(0)
	v_add_f32_e32 v91, v91, v102
	ds_bpermute_b32 v102, v128, v91
	s_waitcnt lgkmcnt(0)
	v_add_f32_e32 v91, v91, v102
	v_add_f32_e32 v91, 0x358637bd, v91
	v_cmp_gt_f32_e32 vcc, s78, v91
	v_mul_f32_e32 v102, 0x4b800000, v91
	s_nop 0
	v_cndmask_b32_e32 v91, v91, v102, vcc
	v_rsq_f32_e32 v91, v91
	s_nop 0
	v_mul_f32_e32 v102, 0x45800000, v91
	v_cndmask_b32_e32 v91, v91, v102, vcc
	v_mul_f32_e32 v102, 0x3db504f3, v91
	v_pk_mul_f32 v[104:105], v[76:77], v[102:103] op_sel_hi:[1,0]
	v_pk_mul_f32 v[106:107], v[78:79], v[102:103] op_sel_hi:[1,0]
	v_pk_mul_f32 v[132:133], v[80:81], v[102:103] op_sel_hi:[1,0]
	v_pk_mul_f32 v[134:135], v[82:83], v[102:103] op_sel_hi:[1,0]
	v_pk_mul_f32 v[84:85], v[84:85], v[102:103] op_sel_hi:[1,0]
	v_pk_mul_f32 v[86:87], v[86:87], v[102:103] op_sel_hi:[1,0]
	v_pk_mul_f32 v[100:101], v[100:101], v[102:103] op_sel_hi:[1,0]
	v_pk_mul_f32 v[98:99], v[98:99], v[102:103] op_sel_hi:[1,0]
	v_cvt_pk_bf16_f32 v76, v104, v105
	v_cvt_pk_bf16_f32 v77, v106, v107
	v_cvt_pk_bf16_f32 v78, v132, v133
	v_cvt_pk_bf16_f32 v79, v134, v135
	v_cvt_pk_bf16_f32 v80, v84, v85
	v_cvt_pk_bf16_f32 v81, v86, v87
	v_cvt_pk_bf16_f32 v82, v100, v101
	v_cvt_pk_bf16_f32 v83, v98, v99
	ds_write_b128 v127, v[76:79] offset:17408
	ds_write_b128 v127, v[80:83] offset:17424
	v_pk_mul_f32 v[76:77], v[90:91], v[104:105] op_sel_hi:[0,1]
	v_pk_mul_f32 v[78:79], v[90:91], v[106:107] op_sel_hi:[0,1]
	v_cvt_pk_bf16_f32 v76, v76, v77
	v_cvt_pk_bf16_f32 v77, v78, v79
	v_pk_mul_f32 v[78:79], v[90:91], v[132:133] op_sel_hi:[0,1]
	v_pk_mul_f32 v[80:81], v[90:91], v[134:135] op_sel_hi:[0,1]
	v_cvt_pk_bf16_f32 v78, v78, v79
	v_cvt_pk_bf16_f32 v79, v80, v81
	v_pk_mul_f32 v[80:81], v[90:91], v[84:85] op_sel_hi:[0,1]
	v_pk_mul_f32 v[82:83], v[90:91], v[86:87] op_sel_hi:[0,1]
	v_cvt_pk_bf16_f32 v80, v80, v81
	v_cvt_pk_bf16_f32 v81, v82, v83
	v_pk_mul_f32 v[82:83], v[90:91], v[100:101] op_sel_hi:[0,1]
	v_pk_mul_f32 v[84:85], v[90:91], v[98:99] op_sel_hi:[0,1]
	v_cvt_pk_bf16_f32 v82, v82, v83
	v_cvt_pk_bf16_f32 v83, v84, v85
	v_add_co_u32_e32 v84, vcc, s0, v92
	s_waitcnt vmcnt(44)
; #define LAS __attribute__((address_space(3)))
; __device__ __forceinline__ unsigned pk2(float lo, float hi) { const f32x2 v = {lo, hi}; const hwbf16x2 r = __builtin_convertvector(v, hwbf16x2); return __builtin_bit_cast(unsigned, r); }
; __device__ __forceinline__ float bf_lo(unsigned v) { return __uint_as_float(v << 16); }
; __device__ __forceinline__ float bf_hi(unsigned v) { return __uint_as_float(v & 0xffff0000u); }
; __device__ __forceinline__ float silu_f(float x) { return x * __builtin_amdgcn_rcpf(1.0f + __expf(-x)); }
; __device__ __forceinline__ void gdn_prep_job3(const float* gdn_conv, const bf16* GQKV, bf16* CHUNK, float* CD, LAS unsigned char* lds, int jb, int jb_next, int rslot, v4u (&xr)[18], int tid, int wave, int lane) {
;     ...
;           for (int wd = 0; wd < 8; ++wd) { const unsigned up = xp[wd >> 2][wd & 3], uc = xc[wd >> 2][wd & 3], un = xn[wd >> 2][wd & 3]; const int e = 2 * wd;
;               const float a0 = silu_f(w0[e] * bf_lo(up) + w1[e] * bf_lo(uc) + w2[e] * bf_lo(un)); const float a1 = silu_f(w0[e + 1] * bf_hi(up) + w1[e + 1] * bf_hi(uc) + w2[e + 1] * bf_hi(un));
;               y[e] = a0; y[e + 1] = a1; ss += a0 * a0 + a1 * a1; }
;           float sc = 1.0f;
;           if (part < 2) { ss += __shfl_xor(ss, 1); ss += __shfl_xor(ss, 2); ss += __shfl_xor(ss, 4); sc = rsqrtf(ss + EPS) * (part == 0 ? 0.08838834764831845f : 1.0f); }
; #pragma unroll
;           for (int e = 0; e < 16; ++e) y[e] *= sc;
;           if (part == 0) {
;               v4u o0, o1; o0.x = pk2(y[0], y[1]); o0.y = pk2(y[2], y[3]); o0.z = pk2(y[4], y[5]); o0.w = pk2(y[6], y[7]); o1.x = pk2(y[8], y[9]); o1.y = pk2(y[10], y[11]); o1.z = pk2(y[12], y[13]); o1.w = pk2(y[14], y[15]);
;               *(LAS v4u*)(qB + i * 136 + seg * 16) = o0; *(LAS v4u*)(qB + i * 136 + seg * 16 + 8) = o1;
;               v4u g0, g1; g0.x = pk2(y[0] * eg_i, y[1] * eg_i); g0.y = pk2(y[2] * eg_i, y[3] * eg_i); g0.z = pk2(y[4] * eg_i, y[5] * eg_i); g0.w = pk2(y[6] * eg_i, y[7] * eg_i);
;               g1.x = pk2(y[8] * eg_i, y[9] * eg_i); g1.y = pk2(y[10] * eg_i, y[11] * eg_i); g1.z = pk2(y[12] * eg_i, y[13] * eg_i); g1.w = pk2(y[14] * eg_i, y[15] * eg_i);
;               *(v4u*)(cb + CH_QD + i * 128 + seg * 16) = g0; *(v4u*)(cb + CH_QD + i * 128 + seg * 16 + 8) = g1;
	v_lshlrev_b32_e32 v92, 16, v35
	v_addc_co_u32_e32 v85, vcc, 0, v93, vcc
	global_store_dwordx4 v[84:85], v[76:79], off
	global_store_dwordx4 v[96:97], v[80:83], off offset:16
	ds_read_b128 v[76:79], v2 offset:1536
	ds_read_b128 v[80:83], v2 offset:1552
	ds_read_b128 v[84:87], v2 offset:1568
	ds_read_b128 v[96:99], v2 offset:1584
	ds_read_b128 v[100:103], v2 offset:2096
	v_and_b32_e32 v93, 0xffff0000, v35
	v_lshlrev_b32_e32 v90, 16, v43
	v_and_b32_e32 v91, 0xffff0000, v43
	v_lshlrev_b32_e32 v106, 16, v31
	s_waitcnt lgkmcnt(0)
	v_pk_mul_f32 v[92:93], v[102:103], v[92:93]
	ds_read_b128 v[102:105], v2 offset:2608
	v_pk_fma_f32 v[90:91], v[98:99], v[90:91], v[92:93]
	v_lshlrev_b32_e32 v92, 16, v51
	v_and_b32_e32 v93, 0xffff0000, v51
	v_lshlrev_b32_e32 v98, 16, v34
	s_waitcnt lgkmcnt(0)
	v_pk_fma_f32 v[90:91], v[104:105], v[92:93], v[90:91]
	v_and_b32_e32 v99, 0xffff0000, v34
	v_mul_f32_e32 v92, 0xbfb8aa3b, v90
	v_mul_f32_e32 v93, 0xbfb8aa3b, v91
	v_exp_f32_e32 v92, v92
	v_exp_f32_e32 v93, v93
	v_pk_mul_f32 v[98:99], v[100:101], v[98:99]
	v_lshlrev_b32_e32 v104, 16, v33
	v_add_f32_e32 v92, 1.0, v92
	v_add_f32_e32 v93, 1.0, v93
	v_rcp_f32_e32 v92, v92
	v_rcp_f32_e32 v93, v93
	v_and_b32_e32 v105, 0xffff0000, v33
	v_and_b32_e32 v107, 0xffff0000, v31
	v_lshlrev_b32_e32 v132, 16, v29
	v_pk_mul_f32 v[90:91], v[90:91], v[92:93]
	v_lshlrev_b32_e32 v92, 16, v42
	v_and_b32_e32 v93, 0xffff0000, v42
	v_pk_fma_f32 v[92:93], v[96:97], v[92:93], v[98:99]
	v_lshlrev_b32_e32 v96, 16, v50
	v_and_b32_e32 v97, 0xffff0000, v50
	v_pk_fma_f32 v[92:93], v[102:103], v[96:97], v[92:93]
	v_mov_b32_e32 v99, v91
	v_mul_f32_e32 v96, 0xbfb8aa3b, v92
	v_mul_f32_e32 v97, 0xbfb8aa3b, v93
	v_exp_f32_e32 v96, v96
	v_exp_f32_e32 v97, v97
	v_lshlrev_b32_e32 v102, 16, v41
	v_and_b32_e32 v103, 0xffff0000, v41
	v_add_f32_e32 v96, 1.0, v96
	v_add_f32_e32 v97, 1.0, v97
	v_rcp_f32_e32 v96, v96
	v_rcp_f32_e32 v97, v97
	v_and_b32_e32 v133, 0xffff0000, v29
	v_pk_mul_f32 v[92:93], v[92:93], v[96:97]
	s_nop 0
	v_mov_b32_e32 v98, v93
	v_mov_b32_e32 v96, v92
	v_mov_b32_e32 v97, v90
	v_pk_mul_f32 v[98:99], v[98:99], v[98:99]
	s_nop 0
	v_pk_fma_f32 v[96:97], v[96:97], v[96:97], v[98:99]
	ds_read_b128 v[98:101], v2 offset:2080
	s_waitcnt lgkmcnt(0)
	v_pk_mul_f32 v[100:101], v[100:101], v[104:105]
	s_nop 0
	v_pk_fma_f32 v[86:87], v[86:87], v[102:103], v[100:101]
	ds_read_b128 v[100:103], v2 offset:2592
	v_lshlrev_b32_e32 v104, 16, v49
	v_and_b32_e32 v105, 0xffff0000, v49
	s_waitcnt lgkmcnt(0)
	v_pk_fma_f32 v[86:87], v[102:103], v[104:105], v[86:87]
	s_nop 0
	v_mul_f32_e32 v102, 0xbfb8aa3b, v86
	v_mul_f32_e32 v103, 0xbfb8aa3b, v87
	v_exp_f32_e32 v102, v102
	v_exp_f32_e32 v103, v103
	v_lshlrev_b32_e32 v104, 16, v32
	v_and_b32_e32 v105, 0xffff0000, v32
	v_add_f32_e32 v102, 1.0, v102
	v_add_f32_e32 v103, 1.0, v103
	v_rcp_f32_e32 v102, v102
	v_rcp_f32_e32 v103, v103
	v_pk_mul_f32 v[98:99], v[98:99], v[104:105]
	v_lshlrev_b32_e32 v104, 16, v39
	v_and_b32_e32 v105, 0xffff0000, v39
	v_pk_mul_f32 v[86:87], v[86:87], v[102:103]
	v_lshlrev_b32_e32 v102, 16, v40
	v_and_b32_e32 v103, 0xffff0000, v40
	v_pk_fma_f32 v[84:85], v[84:85], v[102:103], v[98:99]
	v_lshlrev_b32_e32 v98, 16, v48
	v_and_b32_e32 v99, 0xffff0000, v48
	v_pk_fma_f32 v[84:85], v[100:101], v[98:99], v[84:85]
	v_mov_b32_e32 v101, v87
	v_mul_f32_e32 v98, 0xbfb8aa3b, v84
	v_mul_f32_e32 v99, 0xbfb8aa3b, v85
	v_exp_f32_e32 v98, v98
	v_exp_f32_e32 v99, v99
	v_add_f32_e32 v98, 1.0, v98
	v_add_f32_e32 v99, 1.0, v99
	v_rcp_f32_e32 v98, v98
	v_rcp_f32_e32 v99, v99
	s_nop 0
	v_pk_mul_f32 v[84:85], v[84:85], v[98:99]
	s_nop 0
	v_mov_b32_e32 v100, v85
	v_mov_b32_e32 v98, v84
	v_mov_b32_e32 v99, v86
	v_pk_mul_f32 v[100:101], v[100:101], v[100:101]
	s_nop 0
	v_pk_fma_f32 v[98:99], v[98:99], v[98:99], v[100:101]
	ds_read_b128 v[100:103], v2 offset:2064
	s_waitcnt lgkmcnt(0)
	v_pk_mul_f32 v[102:103], v[102:103], v[106:107]
	s_nop 0
	v_pk_fma_f32 v[82:83], v[82:83], v[104:105], v[102:103]
	ds_read_b128 v[102:105], v2 offset:2576
	v_lshlrev_b32_e32 v106, 16, v47
	v_and_b32_e32 v107, 0xffff0000, v47
	s_waitcnt lgkmcnt(0)
	v_pk_fma_f32 v[82:83], v[104:105], v[106:107], v[82:83]
	s_nop 0
	v_mul_f32_e32 v104, 0xbfb8aa3b, v82
	v_mul_f32_e32 v105, 0xbfb8aa3b, v83
	v_exp_f32_e32 v104, v104
	v_exp_f32_e32 v105, v105
	v_lshlrev_b32_e32 v106, 16, v30
	v_and_b32_e32 v107, 0xffff0000, v30
	v_add_f32_e32 v104, 1.0, v104
	v_add_f32_e32 v105, 1.0, v105
	v_rcp_f32_e32 v104, v104
	v_rcp_f32_e32 v105, v105
	v_pk_mul_f32 v[100:101], v[100:101], v[106:107]
	v_lshlrev_b32_e32 v106, 16, v37
	v_and_b32_e32 v107, 0xffff0000, v37
	v_pk_mul_f32 v[82:83], v[82:83], v[104:105]
	v_lshlrev_b32_e32 v104, 16, v38
	v_and_b32_e32 v105, 0xffff0000, v38
	v_pk_fma_f32 v[80:81], v[80:81], v[104:105], v[100:101]
	v_lshlrev_b32_e32 v100, 16, v46
	v_and_b32_e32 v101, 0xffff0000, v46
	v_pk_fma_f32 v[80:81], v[102:103], v[100:101], v[80:81]
	v_mov_b32_e32 v103, v83
	v_mul_f32_e32 v100, 0xbfb8aa3b, v80
	v_mul_f32_e32 v101, 0xbfb8aa3b, v81
	v_exp_f32_e32 v100, v100
	v_exp_f32_e32 v101, v101
	v_add_f32_e32 v100, 1.0, v100
	v_add_f32_e32 v101, 1.0, v101
	v_rcp_f32_e32 v100, v100
	v_rcp_f32_e32 v101, v101
	s_nop 0
	v_pk_mul_f32 v[80:81], v[80:81], v[100:101]
	s_nop 0
	v_mov_b32_e32 v102, v81
	v_mov_b32_e32 v100, v80
	v_mov_b32_e32 v101, v82
	v_pk_mul_f32 v[102:103], v[102:103], v[102:103]
	s_nop 0
	v_pk_fma_f32 v[100:101], v[100:101], v[100:101], v[102:103]
	ds_read_b128 v[102:105], v2 offset:2048
	s_waitcnt lgkmcnt(0)
	v_pk_mul_f32 v[104:105], v[104:105], v[132:133]
	s_nop 0
	v_pk_fma_f32 v[78:79], v[78:79], v[106:107], v[104:105]
	ds_read_b128 v[104:107], v2 offset:2560
	v_lshlrev_b32_e32 v132, 16, v45
	v_and_b32_e32 v133, 0xffff0000, v45
	s_waitcnt lgkmcnt(0)
; #define LAS __attribute__((address_space(3)))
; __device__ __forceinline__ void gdn_prep_job3(const float* gdn_conv, const bf16* GQKV, bf16* CHUNK, float* CD, LAS unsigned char* lds, int jb, int jb_next, int rslot, v4u (&xr)[18], int tid, int wave, int lane) {
;     ...
;           for (int wd = 0; wd < 8; ++wd) { const unsigned up = xp[wd >> 2][wd & 3], uc = xc[wd >> 2][wd & 3], un = xn[wd >> 2][wd & 3]; const int e = 2 * wd;
;               const float a0 = silu_f(w0[e] * bf_lo(up) + w1[e] * bf_lo(uc) + w2[e] * bf_lo(un)); const float a1 = silu_f(w0[e + 1] * bf_hi(up) + w1[e + 1] * bf_hi(uc) + w2[e + 1] * bf_hi(un));
;               y[e] = a0; y[e + 1] = a1; ss += a0 * a0 + a1 * a1; }
;           float sc = 1.0f;
;           if (part < 2) { ss += __shfl_xor(ss, 1); ss += __shfl_xor(ss, 2); ss += __shfl_xor(ss, 4); sc = rsqrtf(ss + EPS) * (part == 0 ? 0.08838834764831845f : 1.0f); }
; #pragma unroll
;           for (int e = 0; e < 16; ++e) y[e] *= sc;
;           if (part == 0) {
;               v4u o0, o1; o0.x = pk2(y[0], y[1]); o0.y = pk2(y[2], y[3]); o0.z = pk2(y[4], y[5]); o0.w = pk2(y[6], y[7]); o1.x = pk2(y[8], y[9]); o1.y = pk2(y[10], y[11]); o1.z = pk2(y[12], y[13]); o1.w = pk2(y[14], y[15]);
;               *(LAS v4u*)(qB + i * 136 + seg * 16) = o0; *(LAS v4u*)(qB + i * 136 + seg * 16 + 8) = o1;
;               v4u g0, g1; g0.x = pk2(y[0] * eg_i, y[1] * eg_i); g0.y = pk2(y[2] * eg_i, y[3] * eg_i); g0.z = pk2(y[4] * eg_i, y[5] * eg_i); g0.w = pk2(y[6] * eg_i, y[7] * eg_i);
;               g1.x = pk2(y[8] * eg_i, y[9] * eg_i); g1.y = pk2(y[10] * eg_i, y[11] * eg_i); g1.z = pk2(y[12] * eg_i, y[13] * eg_i); g1.w = pk2(y[14] * eg_i, y[15] * eg_i);
;               *(v4u*)(cb + CH_QD + i * 128 + seg * 16) = g0; *(v4u*)(cb + CH_QD + i * 128 + seg * 16 + 8) = g1;
;           } else if (part == 1) {
;               v4u o0, o1; o0.x = pk2(y[0], y[1]); o0.y = pk2(y[2], y[3]); o0.z = pk2(y[4], y[5]); o0.w = pk2(y[6], y[7]); o1.x = pk2(y[8], y[9]); o1.y = pk2(y[10], y[11]); o1.z = pk2(y[12], y[13]); o1.w = pk2(y[14], y[15]);
;               *(LAS v4u*)(kB + i * 136 + seg * 16) = o0; *(LAS v4u*)(kB + i * 136 + seg * 16 + 8) = o1;
; #pragma unroll
;               for (int e = 0; e < 16; ++e) { kdTL[(seg * 16 + e) * 72 + (i ^ (8 * seg))] = (bf16)f2bf(y[e] * kds_i); RT[(128 + seg * 16 + e) * 72 + (i ^ (8 * seg))] = (bf16)f2bf(y[e] * beg_i); }
	v_pk_fma_f32 v[78:79], v[106:107], v[132:133], v[78:79]
	s_nop 0
	v_mul_f32_e32 v106, 0xbfb8aa3b, v78
	v_mul_f32_e32 v107, 0xbfb8aa3b, v79
	v_exp_f32_e32 v106, v106
	v_exp_f32_e32 v107, v107
	v_lshlrev_b32_e32 v132, 16, v28
	v_and_b32_e32 v133, 0xffff0000, v28
	v_add_f32_e32 v106, 1.0, v106
	v_add_f32_e32 v107, 1.0, v107
	v_rcp_f32_e32 v106, v106
	v_rcp_f32_e32 v107, v107
	v_pk_mul_f32 v[102:103], v[102:103], v[132:133]
	v_pk_mul_f32 v[78:79], v[78:79], v[106:107]
	v_lshlrev_b32_e32 v106, 16, v36
	v_and_b32_e32 v107, 0xffff0000, v36
	v_pk_fma_f32 v[76:77], v[76:77], v[106:107], v[102:103]
	v_lshlrev_b32_e32 v102, 16, v44
	v_and_b32_e32 v103, 0xffff0000, v44
	v_pk_fma_f32 v[76:77], v[104:105], v[102:103], v[76:77]
	v_mov_b32_e32 v105, v79
	v_mul_f32_e32 v102, 0xbfb8aa3b, v76
	v_mul_f32_e32 v103, 0xbfb8aa3b, v77
	v_exp_f32_e32 v102, v102
	v_exp_f32_e32 v103, v103
	v_add_f32_e32 v102, 1.0, v102
	v_add_f32_e32 v103, 1.0, v103
	v_rcp_f32_e32 v102, v102
	v_rcp_f32_e32 v103, v103
	s_nop 0
	v_pk_mul_f32 v[76:77], v[76:77], v[102:103]
	s_nop 0
	v_mov_b32_e32 v104, v77
	v_mov_b32_e32 v102, v76
	v_mov_b32_e32 v103, v78
	v_pk_mul_f32 v[104:105], v[104:105], v[104:105]
	s_nop 0
	v_pk_fma_f32 v[102:103], v[102:103], v[102:103], v[104:105]
	s_nop 0
	v_add_f32_e32 v102, v102, v103
	v_add_f32_e32 v100, v102, v100
	v_add_f32_e32 v100, v100, v101
	v_add_f32_e32 v98, v100, v98
	v_add_f32_e32 v98, v98, v99
	v_add_f32_e32 v96, v98, v96
	v_add_f32_e32 v96, v96, v97
	ds_bpermute_b32 v97, v130, v96
	s_waitcnt lgkmcnt(0)
	v_add_f32_e32 v96, v96, v97
	ds_bpermute_b32 v97, v129, v96
	s_waitcnt lgkmcnt(0)
	v_add_f32_e32 v96, v96, v97
	ds_bpermute_b32 v97, v128, v96
	s_waitcnt lgkmcnt(0)
	v_add_f32_e32 v96, v96, v97
	v_add_f32_e32 v96, 0x358637bd, v96
	v_cmp_gt_f32_e32 vcc, s78, v96
	v_mul_f32_e32 v97, 0x4b800000, v96
	s_nop 0
	v_cndmask_b32_e32 v96, v96, v97, vcc
	v_rsq_f32_e32 v96, v96
	s_nop 0
	v_mul_f32_e32 v97, 0x45800000, v96
	v_cndmask_b32_e32 v96, v96, v97, vcc
	v_pk_mul_f32 v[98:99], v[76:77], v[96:97] op_sel_hi:[1,0]
	v_pk_mul_f32 v[100:101], v[78:79], v[96:97] op_sel_hi:[1,0]
	v_pk_mul_f32 v[102:103], v[80:81], v[96:97] op_sel_hi:[1,0]
	v_pk_mul_f32 v[104:105], v[82:83], v[96:97] op_sel_hi:[1,0]
	v_pk_mul_f32 v[84:85], v[84:85], v[96:97] op_sel_hi:[1,0]
	v_pk_mul_f32 v[86:87], v[86:87], v[96:97] op_sel_hi:[1,0]
	v_pk_mul_f32 v[92:93], v[92:93], v[96:97] op_sel_hi:[1,0]
	v_pk_mul_f32 v[90:91], v[90:91], v[96:97] op_sel_hi:[1,0]
	v_cvt_pk_bf16_f32 v76, v98, v99
	v_cvt_pk_bf16_f32 v77, v100, v101
	v_cvt_pk_bf16_f32 v78, v102, v103
	v_cvt_pk_bf16_f32 v79, v104, v105
	v_cvt_pk_bf16_f32 v80, v84, v85
	v_cvt_pk_bf16_f32 v81, v86, v87
	v_cvt_pk_bf16_f32 v82, v92, v93
	v_cvt_pk_bf16_f32 v83, v90, v91
	ds_write_b128 v127, v[76:79]
	ds_write_b128 v127, v[80:83] offset:16
	v_mul_f32_e32 v76, v126, v98
	v_cvt_pk_bf16_f32 v76, v76, s0
	v_add3_u32 v77, s48, v1, v89
	ds_write_b16 v77, v76
	v_mul_f32_e32 v76, v125, v98
	v_cvt_pk_bf16_f32 v76, v76, s0
	v_add3_u32 v78, 0, v89, v1
	ds_write_b16 v78, v76 offset:53248
	v_mul_f32_e32 v76, v126, v99
	v_cvt_pk_bf16_f32 v76, v76, s0
	ds_write_b16 v77, v76 offset:144
	v_mul_f32_e32 v76, v125, v99
	v_cvt_pk_bf16_f32 v76, v76, s0
	ds_write_b16 v78, v76 offset:53392
	v_mul_f32_e32 v76, v126, v100
	v_cvt_pk_bf16_f32 v76, v76, s0
	ds_write_b16 v77, v76 offset:288
	v_mul_f32_e32 v76, v125, v100
	v_cvt_pk_bf16_f32 v76, v76, s0
	ds_write_b16 v78, v76 offset:53536
	v_mul_f32_e32 v76, v126, v101
	v_cvt_pk_bf16_f32 v76, v76, s0
	ds_write_b16 v77, v76 offset:432
	v_mul_f32_e32 v76, v125, v101
	v_cvt_pk_bf16_f32 v76, v76, s0
	ds_write_b16 v78, v76 offset:53680
	v_mul_f32_e32 v76, v126, v102
	v_cvt_pk_bf16_f32 v76, v76, s0
	ds_write_b16 v77, v76 offset:576
	v_mul_f32_e32 v76, v125, v102
	v_cvt_pk_bf16_f32 v76, v76, s0
	ds_write_b16 v78, v76 offset:53824
	v_mul_f32_e32 v76, v126, v103
	v_cvt_pk_bf16_f32 v76, v76, s0
	ds_write_b16 v77, v76 offset:720
	v_mul_f32_e32 v76, v125, v103
	v_cvt_pk_bf16_f32 v76, v76, s0
	ds_write_b16 v78, v76 offset:53968
	v_mul_f32_e32 v76, v126, v104
	v_cvt_pk_bf16_f32 v76, v76, s0
	ds_write_b16 v77, v76 offset:864
	v_mul_f32_e32 v76, v125, v104
	v_cvt_pk_bf16_f32 v76, v76, s0
	ds_write_b16 v78, v76 offset:54112
	v_mul_f32_e32 v76, v126, v105
	v_cvt_pk_bf16_f32 v76, v76, s0
	ds_write_b16 v77, v76 offset:1008
	v_mul_f32_e32 v76, v125, v105
	v_cvt_pk_bf16_f32 v76, v76, s0
	ds_write_b16 v78, v76 offset:54256
	v_mul_f32_e32 v76, v126, v84
	v_cvt_pk_bf16_f32 v76, v76, s0
	ds_write_b16 v77, v76 offset:1152
	v_mul_f32_e32 v76, v125, v84
	v_cvt_pk_bf16_f32 v76, v76, s0
	ds_write_b16 v78, v76 offset:54400
	v_mul_f32_e32 v76, v126, v85
	v_cvt_pk_bf16_f32 v76, v76, s0
	ds_write_b16 v77, v76 offset:1296
	v_mul_f32_e32 v76, v125, v85
	v_cvt_pk_bf16_f32 v76, v76, s0
	ds_write_b16 v78, v76 offset:54544
	v_mul_f32_e32 v76, v126, v86
	v_cvt_pk_bf16_f32 v76, v76, s0
	ds_write_b16 v77, v76 offset:1440
	v_mul_f32_e32 v76, v125, v86
	v_cvt_pk_bf16_f32 v76, v76, s0
	ds_write_b16 v78, v76 offset:54688
	v_mul_f32_e32 v76, v126, v87
	v_cvt_pk_bf16_f32 v76, v76, s0
	ds_write_b16 v77, v76 offset:1584
	v_mul_f32_e32 v76, v125, v87
	v_cvt_pk_bf16_f32 v76, v76, s0
	ds_write_b16 v78, v76 offset:54832
	v_mul_f32_e32 v76, v126, v92
	v_cvt_pk_bf16_f32 v76, v76, s0
	ds_write_b16 v77, v76 offset:1728
	v_mul_f32_e32 v76, v125, v92
	v_cvt_pk_bf16_f32 v76, v76, s0
	ds_write_b16 v78, v76 offset:54976
	v_mul_f32_e32 v76, v126, v93
	v_cvt_pk_bf16_f32 v76, v76, s0
	ds_write_b16 v77, v76 offset:1872
	v_mul_f32_e32 v76, v125, v93
	v_cvt_pk_bf16_f32 v76, v76, s0
	ds_write_b16 v78, v76 offset:55120
	v_mul_f32_e32 v76, v126, v90
	v_cvt_pk_bf16_f32 v76, v76, s0
	ds_write_b16 v77, v76 offset:2016
	v_mul_f32_e32 v76, v125, v90
	v_cvt_pk_bf16_f32 v76, v76, s0
	ds_write_b16 v78, v76 offset:55264
	v_mul_f32_e32 v76, v126, v91
	v_cvt_pk_bf16_f32 v76, v76, s0
	ds_write_b16 v77, v76 offset:2160
	v_mul_f32_e32 v76, v125, v91
	v_cvt_pk_bf16_f32 v76, v76, s0
	ds_write_b16 v78, v76 offset:55408
	ds_read_b128 v[90:93], v2 offset:3072
	ds_read_b128 v[84:87], v2 offset:3088
	ds_read_b128 v[80:83], v2 offset:3104
	ds_read_b128 v[76:79], v2 offset:3120
	ds_read_b128 v[96:99], v2 offset:3584
	s_waitcnt vmcnt(45)
; __device__ __forceinline__ unsigned f2bf(float f) { return pk2(f, f) & 0xffffu; }
; __device__ __forceinline__ float bf_lo(unsigned v) { return __uint_as_float(v << 16); }
; __device__ __forceinline__ float bf_hi(unsigned v) { return __uint_as_float(v & 0xffff0000u); }
; __device__ __forceinline__ float silu_f(float x) { return x * __builtin_amdgcn_rcpf(1.0f + __expf(-x)); }
; __device__ __forceinline__ void gdn_prep_job3(const float* gdn_conv, const bf16* GQKV, bf16* CHUNK, float* CD, LAS unsigned char* lds, int jb, int jb_next, int rslot, v4u (&xr)[18], int tid, int wave, int lane) {
;     ...
;           for (int wd = 0; wd < 8; ++wd) { const unsigned up = xp[wd >> 2][wd & 3], uc = xc[wd >> 2][wd & 3], un = xn[wd >> 2][wd & 3]; const int e = 2 * wd;
;               const float a0 = silu_f(w0[e] * bf_lo(up) + w1[e] * bf_lo(uc) + w2[e] * bf_lo(un)); const float a1 = silu_f(w0[e + 1] * bf_hi(up) + w1[e + 1] * bf_hi(uc) + w2[e + 1] * bf_hi(un));
;               y[e] = a0; y[e + 1] = a1; ss += a0 * a0 + a1 * a1; }
;     ...
;           } else {
; #pragma unroll
;               for (int e = 0; e < 16; ++e) RT[(seg * 16 + e) * 72 + (i ^ (8 * seg))] = (bf16)f2bf(y[e] * beta_i);
	v_lshlrev_b32_e32 v101, 16, v52
	s_waitcnt vmcnt(44)
	v_lshlrev_b32_e32 v100, 16, v64
	v_add3_u32 v1, 0, v1, v89
	s_waitcnt lgkmcnt(0)
	v_mul_f32_e32 v96, v96, v101
	v_fmac_f32_e32 v96, v90, v100
	ds_read_b128 v[100:103], v2 offset:4096
	v_lshlrev_b32_e32 v90, 16, v68
	s_waitcnt lgkmcnt(0)
	v_fmac_f32_e32 v96, v100, v90
	v_mul_f32_e32 v90, 0xbfb8aa3b, v96
	v_exp_f32_e32 v90, v90
	v_and_b32_e32 v100, 0xffff0000, v52
	v_mul_f32_e32 v97, v97, v100
	v_lshlrev_b32_e32 v100, 16, v66
	v_add_f32_e32 v90, 1.0, v90
	v_rcp_f32_e32 v90, v90
	s_nop 0
	v_mul_f32_e32 v90, v96, v90
	v_and_b32_e32 v96, 0xffff0000, v64
	v_fmac_f32_e32 v97, v91, v96
	v_and_b32_e32 v91, 0xffff0000, v68
	v_fmac_f32_e32 v97, v101, v91
	v_mul_f32_e32 v91, 0xbfb8aa3b, v97
	v_exp_f32_e32 v91, v91
	v_lshlrev_b32_e32 v96, 16, v65
	v_lshlrev_b32_e32 v101, 16, v54
	v_add_f32_e32 v91, 1.0, v91
	v_rcp_f32_e32 v91, v91
	s_nop 0
	v_mul_f32_e32 v91, v97, v91
	v_lshlrev_b32_e32 v97, 16, v53
	v_mul_f32_e32 v97, v98, v97
	v_fmac_f32_e32 v97, v92, v96
	v_lshlrev_b32_e32 v92, 16, v69
	v_fmac_f32_e32 v97, v102, v92
	v_mul_f32_e32 v92, 0xbfb8aa3b, v97
	v_exp_f32_e32 v92, v92
	v_and_b32_e32 v96, 0xffff0000, v65
	v_add_f32_e32 v92, 1.0, v92
	v_rcp_f32_e32 v92, v92
	s_nop 0
	v_mul_f32_e32 v92, v97, v92
	v_and_b32_e32 v97, 0xffff0000, v53
	v_mul_f32_e32 v97, v99, v97
	v_fmac_f32_e32 v97, v93, v96
	v_and_b32_e32 v93, 0xffff0000, v69
	v_fmac_f32_e32 v97, v103, v93
	v_mul_f32_e32 v93, 0xbfb8aa3b, v97
	v_exp_f32_e32 v93, v93
	s_nop 0
	v_add_f32_e32 v93, 1.0, v93
	v_rcp_f32_e32 v93, v93
	s_nop 0
	v_mul_f32_e32 v93, v97, v93
	ds_read_b128 v[96:99], v2 offset:3600
	s_waitcnt lgkmcnt(0)
	v_mul_f32_e32 v96, v96, v101
	v_fmac_f32_e32 v96, v84, v100
	ds_read_b128 v[100:103], v2 offset:4112
	v_lshlrev_b32_e32 v84, 16, v70
	s_waitcnt lgkmcnt(0)
	v_fmac_f32_e32 v96, v100, v84
	v_mul_f32_e32 v84, 0xbfb8aa3b, v96
	v_exp_f32_e32 v84, v84
	v_and_b32_e32 v100, 0xffff0000, v54
	v_mul_f32_e32 v97, v97, v100
	v_lshlrev_b32_e32 v100, 16, v60
	v_add_f32_e32 v84, 1.0, v84
	v_rcp_f32_e32 v84, v84
	s_nop 0
	v_mul_f32_e32 v84, v96, v84
	v_and_b32_e32 v96, 0xffff0000, v66
	v_fmac_f32_e32 v97, v85, v96
	v_and_b32_e32 v85, 0xffff0000, v70
	v_fmac_f32_e32 v97, v101, v85
	v_mul_f32_e32 v85, 0xbfb8aa3b, v97
	v_exp_f32_e32 v85, v85
	v_lshlrev_b32_e32 v96, 16, v67
	v_lshlrev_b32_e32 v101, 16, v56
	v_add_f32_e32 v85, 1.0, v85
	v_rcp_f32_e32 v85, v85
	s_nop 0
	v_mul_f32_e32 v85, v97, v85
	v_lshlrev_b32_e32 v97, 16, v55
	v_mul_f32_e32 v97, v98, v97
	v_fmac_f32_e32 v97, v86, v96
	v_lshlrev_b32_e32 v86, 16, v71
	v_fmac_f32_e32 v97, v102, v86
	v_mul_f32_e32 v86, 0xbfb8aa3b, v97
	v_exp_f32_e32 v86, v86
	v_and_b32_e32 v96, 0xffff0000, v67
	v_add_f32_e32 v86, 1.0, v86
	v_rcp_f32_e32 v86, v86
	s_nop 0
	v_mul_f32_e32 v86, v97, v86
	v_and_b32_e32 v97, 0xffff0000, v55
	v_mul_f32_e32 v97, v99, v97
	v_fmac_f32_e32 v97, v87, v96
	v_and_b32_e32 v87, 0xffff0000, v71
	v_fmac_f32_e32 v97, v103, v87
	v_mul_f32_e32 v87, 0xbfb8aa3b, v97
	v_exp_f32_e32 v87, v87
	s_nop 0
	v_add_f32_e32 v87, 1.0, v87
	v_rcp_f32_e32 v87, v87
	s_nop 0
	v_mul_f32_e32 v87, v97, v87
	ds_read_b128 v[96:99], v2 offset:3616
	s_waitcnt lgkmcnt(0)
	v_mul_f32_e32 v96, v96, v101
	v_fmac_f32_e32 v96, v80, v100
	ds_read_b128 v[100:103], v2 offset:4128
	v_lshlrev_b32_e32 v80, 16, v72
	s_waitcnt lgkmcnt(0)
	v_fmac_f32_e32 v96, v100, v80
	v_mul_f32_e32 v80, 0xbfb8aa3b, v96
	v_exp_f32_e32 v80, v80
	s_nop 0
	v_add_f32_e32 v80, 1.0, v80
	v_rcp_f32_e32 v80, v80
	s_nop 0
	v_mul_f32_e32 v100, v96, v80
	v_and_b32_e32 v96, 0xffff0000, v56
	v_and_b32_e32 v80, 0xffff0000, v60
	v_mul_f32_e32 v96, v97, v96
	v_fmac_f32_e32 v96, v81, v80
	v_and_b32_e32 v80, 0xffff0000, v72
	v_fmac_f32_e32 v96, v101, v80
	v_mul_f32_e32 v80, 0xbfb8aa3b, v96
	v_exp_f32_e32 v80, v80
	v_lshlrev_b32_e32 v81, 16, v57
	v_mul_f32_e32 v81, v98, v81
	v_lshlrev_b32_e32 v97, 16, v58
	v_add_f32_e32 v80, 1.0, v80
	v_rcp_f32_e32 v80, v80
	s_nop 0
	v_mul_f32_e32 v101, v96, v80
	v_lshlrev_b32_e32 v80, 16, v61
	v_fmac_f32_e32 v81, v82, v80
	v_lshlrev_b32_e32 v80, 16, v73
	v_fmac_f32_e32 v81, v102, v80
	v_mul_f32_e32 v80, 0xbfb8aa3b, v81
	v_exp_f32_e32 v80, v80
	v_lshlrev_b32_e32 v96, 16, v62
	v_add_f32_e32 v80, 1.0, v80
	v_rcp_f32_e32 v80, v80
	s_nop 0
	v_mul_f32_e32 v102, v81, v80
	v_and_b32_e32 v81, 0xffff0000, v57
	v_and_b32_e32 v80, 0xffff0000, v61
	v_mul_f32_e32 v81, v99, v81
	v_fmac_f32_e32 v81, v83, v80
	v_and_b32_e32 v80, 0xffff0000, v73
	v_fmac_f32_e32 v81, v103, v80
	v_mul_f32_e32 v80, 0xbfb8aa3b, v81
	v_exp_f32_e32 v80, v80
	s_nop 0
	v_add_f32_e32 v80, 1.0, v80
	v_rcp_f32_e32 v80, v80
	s_nop 0
	v_mul_f32_e32 v103, v81, v80
	ds_read_b128 v[80:83], v2 offset:3632
	s_waitcnt lgkmcnt(0)
; __device__ __forceinline__ void gdn_prep_job3(const float* gdn_conv, const bf16* GQKV, bf16* CHUNK, float* CD, LAS unsigned char* lds, int jb, int jb_next, int rslot, v4u (&xr)[18], int tid, int wave, int lane) {
;     ...
;           for (int wd = 0; wd < 8; ++wd) { const unsigned up = xp[wd >> 2][wd & 3], uc = xc[wd >> 2][wd & 3], un = xn[wd >> 2][wd & 3]; const int e = 2 * wd;
;               const float a0 = silu_f(w0[e] * bf_lo(up) + w1[e] * bf_lo(uc) + w2[e] * bf_lo(un)); const float a1 = silu_f(w0[e + 1] * bf_hi(up) + w1[e + 1] * bf_hi(uc) + w2[e + 1] * bf_hi(un));
;               y[e] = a0; y[e + 1] = a1; ss += a0 * a0 + a1 * a1; }
;           float sc = 1.0f;
;           if (part < 2) { ss += __shfl_xor(ss, 1); ss += __shfl_xor(ss, 2); ss += __shfl_xor(ss, 4); sc = rsqrtf(ss + EPS) * (part == 0 ? 0.08838834764831845f : 1.0f); }
; #pragma unroll
;           for (int e = 0; e < 16; ++e) y[e] *= sc;
;           if (part == 0) {
;               v4u o0, o1; o0.x = pk2(y[0], y[1]); o0.y = pk2(y[2], y[3]); o0.z = pk2(y[4], y[5]); o0.w = pk2(y[6], y[7]); o1.x = pk2(y[8], y[9]); o1.y = pk2(y[10], y[11]); o1.z = pk2(y[12], y[13]); o1.w = pk2(y[14], y[15]);
;               *(LAS v4u*)(qB + i * 136 + seg * 16) = o0; *(LAS v4u*)(qB + i * 136 + seg * 16 + 8) = o1;
;               v4u g0, g1; g0.x = pk2(y[0] * eg_i, y[1] * eg_i); g0.y = pk2(y[2] * eg_i, y[3] * eg_i); g0.z = pk2(y[4] * eg_i, y[5] * eg_i); g0.w = pk2(y[6] * eg_i, y[7] * eg_i);
;               g1.x = pk2(y[8] * eg_i, y[9] * eg_i); g1.y = pk2(y[10] * eg_i, y[11] * eg_i); g1.z = pk2(y[12] * eg_i, y[13] * eg_i); g1.w = pk2(y[14] * eg_i, y[15] * eg_i);
;               *(v4u*)(cb + CH_QD + i * 128 + seg * 16) = g0; *(v4u*)(cb + CH_QD + i * 128 + seg * 16 + 8) = g1;
;           } else if (part == 1) {
;               v4u o0, o1; o0.x = pk2(y[0], y[1]); o0.y = pk2(y[2], y[3]); o0.z = pk2(y[4], y[5]); o0.w = pk2(y[6], y[7]); o1.x = pk2(y[8], y[9]); o1.y = pk2(y[10], y[11]); o1.z = pk2(y[12], y[13]); o1.w = pk2(y[14], y[15]);
;               *(LAS v4u*)(kB + i * 136 + seg * 16) = o0; *(LAS v4u*)(kB + i * 136 + seg * 16 + 8) = o1;
; #pragma unroll
;               for (int e = 0; e < 16; ++e) { kdTL[(seg * 16 + e) * 72 + (i ^ (8 * seg))] = (bf16)f2bf(y[e] * kds_i); RT[(128 + seg * 16 + e) * 72 + (i ^ (8 * seg))] = (bf16)f2bf(y[e] * beg_i); }
;           } else {
; #pragma unroll
	v_mul_f32_e32 v80, v80, v97
	v_fmac_f32_e32 v80, v76, v96
	ds_read_b128 v[96:99], v2 offset:4144
	v_lshlrev_b32_e32 v2, 16, v74
	v_and_b32_e32 v76, 0xffff0000, v62
	s_waitcnt lgkmcnt(0)
	v_fmac_f32_e32 v80, v96, v2
	v_mul_f32_e32 v2, 0xbfb8aa3b, v80
	v_exp_f32_e32 v2, v2
	s_nop 0
	v_add_f32_e32 v2, 1.0, v2
	v_rcp_f32_e32 v2, v2
	s_nop 0
	v_mul_f32_e32 v2, v80, v2
	v_and_b32_e32 v80, 0xffff0000, v58
	v_mul_f32_e32 v80, v81, v80
	v_fmac_f32_e32 v80, v77, v76
	v_and_b32_e32 v76, 0xffff0000, v74
	v_fmac_f32_e32 v80, v97, v76
	v_mul_f32_e32 v76, 0xbfb8aa3b, v80
	v_exp_f32_e32 v76, v76
	v_lshlrev_b32_e32 v77, 16, v63
	v_mul_f32_e32 v2, v3, v2
	v_cvt_pk_bf16_f32 v2, v2, s0
	v_add_f32_e32 v76, 1.0, v76
	v_rcp_f32_e32 v76, v76
	ds_write_b16 v1, v2 offset:36544
	v_mul_f32_e32 v76, v80, v76
	v_lshlrev_b32_e32 v80, 16, v59
	v_mul_f32_e32 v80, v82, v80
	v_fmac_f32_e32 v80, v78, v77
	v_lshlrev_b32_e32 v77, 16, v75
	v_fmac_f32_e32 v80, v98, v77
	v_mul_f32_e32 v77, 0xbfb8aa3b, v80
	v_exp_f32_e32 v77, v77
	v_and_b32_e32 v78, 0xffff0000, v63
	v_mul_f32_e32 v2, v3, v76
	v_cvt_pk_bf16_f32 v2, v2, s0
	v_add_f32_e32 v77, 1.0, v77
	v_rcp_f32_e32 v77, v77
	ds_write_b16 v1, v2 offset:36688
	v_mul_f32_e32 v77, v80, v77
	v_and_b32_e32 v80, 0xffff0000, v59
	v_mul_f32_e32 v80, v83, v80
	v_fmac_f32_e32 v80, v79, v78
	v_mul_f32_e32 v79, v3, v90
	v_cvt_pk_bf16_f32 v79, v79, s0
	ds_write_b16 v1, v79 offset:34816
	v_mul_f32_e32 v79, v3, v91
	v_cvt_pk_bf16_f32 v79, v79, s0
	ds_write_b16 v1, v79 offset:34960
	v_mul_f32_e32 v79, v3, v92
	v_cvt_pk_bf16_f32 v79, v79, s0
	ds_write_b16 v1, v79 offset:35104
	v_mul_f32_e32 v79, v3, v93
	v_cvt_pk_bf16_f32 v79, v79, s0
	ds_write_b16 v1, v79 offset:35248
	v_mul_f32_e32 v79, v3, v84
	v_and_b32_e32 v78, 0xffff0000, v75
	v_cvt_pk_bf16_f32 v79, v79, s0
	v_fmac_f32_e32 v80, v99, v78
	ds_write_b16 v1, v79 offset:35392
	v_mul_f32_e32 v79, v3, v85
	v_mul_f32_e32 v78, 0xbfb8aa3b, v80
	v_cvt_pk_bf16_f32 v79, v79, s0
	v_exp_f32_e32 v78, v78
	ds_write_b16 v1, v79 offset:35536
	v_mul_f32_e32 v79, v3, v86
	v_cvt_pk_bf16_f32 v79, v79, s0
	ds_write_b16 v1, v79 offset:35680
	v_mul_f32_e32 v79, v3, v87
	v_cvt_pk_bf16_f32 v79, v79, s0
	v_add_f32_e32 v78, 1.0, v78
	ds_write_b16 v1, v79 offset:35824
	v_mul_f32_e32 v79, v3, v100
	v_rcp_f32_e32 v78, v78
	v_cvt_pk_bf16_f32 v79, v79, s0
	ds_write_b16 v1, v79 offset:35968
	v_mul_f32_e32 v79, v3, v101
	v_cvt_pk_bf16_f32 v79, v79, s0
	ds_write_b16 v1, v79 offset:36112
	v_mul_f32_e32 v79, v3, v102
	v_mul_f32_e32 v2, v3, v77
	v_mul_f32_e32 v78, v80, v78
	v_cvt_pk_bf16_f32 v79, v79, s0
	v_cvt_pk_bf16_f32 v2, v2, s0
	ds_write_b16 v1, v79 offset:36256
	v_mul_f32_e32 v79, v3, v103
	ds_write_b16 v1, v2 offset:36832
	v_mul_f32_e32 v2, v3, v78
	v_cvt_pk_bf16_f32 v79, v79, s0
	v_cvt_pk_bf16_f32 v2, v2, s0
	ds_write_b16 v1, v79 offset:36400
	ds_write_b16 v1, v2 offset:36976
	s_waitcnt lgkmcnt(0)
	s_barrier
	s_cbranch_scc1 .LBB0_273
	s_lshl_b32 s76, s1, 1
	s_and_b32 s76, s76, 0x780
	s_movk_i32 s98, 0x480
	v_cmp_gt_i32_e32 vcc, s98, v88
	s_and_saveexec_b64 s[98:99], vcc
	s_cbranch_execz .Ltaps_done
	v_max_i32_e32 v1, 0x280, v88
	v_sub_u32_e32 v1, v1, v88
	v_add_u32_e32 v3, 0x1ff, v1
	s_movk_i32 s18, 0x1ff
	v_and_b32_e32 v76, 0x7f, v88
	v_cmp_lt_u32_e32 vcc, s18, v3
	s_mov_b64 s[20:21], 0
	s_and_saveexec_b64 s[18:19], vcc
	s_xor_b64 s[18:19], exec, s[18:19]
	s_cbranch_execz .LBB0_267
	v_lshrrev_b32_e32 v1, 9, v3
	v_add_u32_e32 v3, 1, v1
	v_and_b32_e32 v78, 0xfffffe, v3
	v_add_u32_e32 v89, 0x200, v88
	v_or_b32_e32 v2, s76, v76
	v_readlane_b32 s20, v253, 53
	v_mov_b32_e32 v1, v2
	v_mov_b32_e32 v80, v78
	v_lshl_add_u32 v79, v88, 2, s20
	s_mov_b64 s[20:21], 0
	v_mov_b64_e32 v[76:77], v[88:89]

; #define LAS __attribute__((address_space(3)))
; __device__ __forceinline__ void prep_issue(const bf16* GQKV, const float* gdn_conv, LAS float* wL, int jb, int tid, v4u (&xr)[18]) {
;     const int n = jb & 63, h = (jb >> 6) & 15, b = (jb >> 10) & 1, d = jb >> 11;
;     const int i = tid >> 3, seg = tid & 7; const int tok = d ? SEQ - 1 - (n * 64 + i) : n * 64 + i; const size_t m = (size_t)b * SEQ + tok;
;     const bf16* row = GQKV + m * 6144 + h * 128 + seg * 16; const v4u zero = {0u, 0u, 0u, 0u};
; #pragma unroll
;     for (int part = 0; part < 3; ++part) { const bf16* rp = row + part * 2048;
;         xr[part * 6 + 2] = *(const v4u*)rp; xr[part * 6 + 3] = *(const v4u*)(rp + 8); xr[part * 6 + 0] = zero; xr[part * 6 + 1] = zero; xr[part * 6 + 4] = zero; xr[part * 6 + 5] = zero;
;         if (tok > 0) { xr[part * 6 + 0] = *(const v4u*)(rp - 6144); xr[part * 6 + 1] = *(const v4u*)(rp - 6144 + 8); }
;         if (tok < SEQ - 1) { xr[part * 6 + 4] = *(const v4u*)(rp + 6144); xr[part * 6 + 5] = *(const v4u*)(rp + 6144 + 8); } }
.Ltaps_done:
	s_or_b64 exec, exec, s[98:99]
	s_cmpk_lt_u32 s1, 0x800
	s_cselect_b64 vcc, -1, 0
	s_lshl_b32 s0, s1, 6
	s_and_b32 s0, s0, 0xfc0
	s_xor_b32 s18, s0, 0xfff
	v_sub_u32_e32 v1, s18, v124
	v_add_u32_e32 v2, s0, v124
	s_lshl_b32 s0, s1, 2
	v_cndmask_b32_e32 v1, v1, v2, vcc
	s_and_b32 s0, s0, 0x1000
	v_add_u32_e32 v4, s0, v1
	v_mov_b64_e32 v[2:3], s[2:3]
	s_movk_i32 s0, 0x3000
	v_mad_i64_i32 v[2:3], s[18:19], v4, s0, v[2:3]
	s_lshl_b32 s0, s1, 1
	s_and_b32 s76, s0, 0x780
	s_lshl_b32 s94, s76, 1
	v_lshlrev_b32_e32 v4, 5, v88
	v_lshl_add_u64 v[2:3], v[2:3], 0, s[94:95]
	v_and_b32_e32 v4, 0xe0, v4
	v_mov_b32_e32 v5, v0
	v_lshl_add_u64 v[76:77], v[2:3], 0, v[4:5]
	global_load_dwordx4 v[4:7], v[76:77], off offset:16
	global_load_dwordx4 v[8:11], v[76:77], off
	v_mov_b32_e32 v14, v0
	v_mov_b32_e32 v15, v0
	v_mov_b32_e32 v12, v0
	v_mov_b32_e32 v13, v0
	v_mov_b64_e32 v[18:19], v[14:15]
	v_mov_b64_e32 v[22:23], v[14:15]
	v_cmp_lt_i32_e64 s[18:19], 0, v1
	v_mov_b64_e32 v[16:17], v[12:13]
	v_mov_b64_e32 v[20:21], v[12:13]
	s_and_saveexec_b64 s[0:1], s[18:19]
	s_cbranch_execz .LBB0_252
	s_movk_i32 s20, 0xd000
	v_add_co_u32_e32 v16, vcc, 0xffffd000, v76
	s_mov_b32 s21, -1
	s_nop 0
	v_addc_co_u32_e32 v17, vcc, -1, v77, vcc
	v_lshl_add_u64 v[2:3], v[76:77], 0, s[20:21]
	global_load_dwordx4 v[16:19], v[16:17], off
	s_nop 0
	global_load_dwordx4 v[20:23], v[2:3], off offset:16
